# slc_block tail rewritten: the 8 o_win row loads and LDS reads issued up front with counted waits instead of a load + vmcnt(0) per row
# baseline (speedup 1.0000x reference)
; DI float bflo(unsigned w) { return __uint_as_float(w << 16); }
; DI float bfhi(unsigned w) { return __uint_as_float(w & 0xffff0000u); }
; DI void slc_block(const Params& p, int it, int tid, int wid, int lane) {
;     ...
;     int l3 = lane; asm volatile("" : "+v"(l3));
;     const int srow = l3 >> 4, sch = l3 & 15;
; #pragma unroll
;     for (int i = 0; i < 8; ++i) {
;       const int row = srow + 4 * i;
;       const uint4 v = lds_row_chunk(wl, row, sch);
;       const float2 gg = reinterpret_cast<const float2*>(wl + 8192)[row];
;       const size_t ro = (tokbase + t0 + 4 * wid + (row >> 3)) * 2048 + (size_t)(8 * g + (row & 7)) * 128 + sch * 8;
;       const uint4 ww = *reinterpret_cast<const uint4*>((const u16*)(p.ws + OFF_R3) + ro);
;       uint4 y;
;       y.x = pk2(bflo(v.x) + gg.y * bflo(ww.x), bfhi(v.x) + gg.y * bfhi(ww.x));
;       y.y = pk2(bflo(v.y) + gg.y * bflo(ww.y), bfhi(v.y) + gg.y * bfhi(ww.y));
;       y.z = pk2(bflo(v.z) + gg.y * bflo(ww.z), bfhi(v.z) + gg.y * bfhi(ww.z));
;       y.w = pk2(bflo(v.w) + gg.y * bflo(ww.w), bfhi(v.w) + gg.y * bfhi(ww.w));
;       *reinterpret_cast<uint4*>((u16*)(p.ws + OFF_YB) + ro) = y;
.LBB0_161:
	s_or_b64 exec, exec, s[2:3]
	s_add_i32 s29, s29, s47
	v_and_b32_e32 v5, 63, v239
	v_ashrrev_i32_e32 v3, 4, v5
	v_and_b32_e32 v2, 15, v5
	v_lshlrev_b32_e32 v0, 3, v2
	v_lshl_add_u32 v4, v3, 3, v244
	ds_read_b32 v96, v4 offset:8196
	ds_read_b32 v98, v4 offset:8228
	ds_read_b32 v100, v4 offset:8260
	ds_read_b32 v102, v4 offset:8292
	ds_read_b32 v104, v4 offset:8324
	ds_read_b32 v106, v4 offset:8356
	ds_read_b32 v108, v4 offset:8388
	ds_read_b32 v110, v4 offset:8420
	s_waitcnt lgkmcnt(7)
	v_mov_b32_e32 v10, v3
	v_ashrrev_i32_e32 v6, 3, v10
	v_ashrrev_i32_e32 v7, 31, v6
	v_lshl_add_u64 v[6:7], v[176:177], 0, v[6:7]
	v_and_or_b32 v8, v10, 7, s85
	v_lshlrev_b64 v[6:7], 11, v[6:7]
	v_lshlrev_b32_e32 v8, 7, v8
	v_or3_b32 v6, v6, v8, v0
	v_lshlrev_b64 v[16:17], 1, v[6:7]
	v_lshl_add_u64 v[6:7], s[86:87], 0, v[16:17]
	global_load_dwordx4 v[32:35], v[6:7], off
	v_bitop3_b32 v8, v10, v2, 15 bitop3:0x6c
	v_lshlrev_b32_e32 v9, 8, v10
	v_lshlrev_b32_e32 v8, 4, v8
	v_add3_u32 v8, v244, v9, v8
	ds_read_b128 v[64:67], v8
	v_add_u32_e32 v10, 4, v3
	v_ashrrev_i32_e32 v6, 3, v10
	v_ashrrev_i32_e32 v7, 31, v6
	v_lshl_add_u64 v[6:7], v[176:177], 0, v[6:7]
	v_and_or_b32 v8, v10, 7, s85
	v_lshlrev_b64 v[6:7], 11, v[6:7]
	v_lshlrev_b32_e32 v8, 7, v8
	v_or3_b32 v6, v6, v8, v0
	v_lshlrev_b64 v[18:19], 1, v[6:7]
	v_lshl_add_u64 v[6:7], s[86:87], 0, v[18:19]
	global_load_dwordx4 v[36:39], v[6:7], off
	v_bitop3_b32 v8, v10, v2, 15 bitop3:0x6c
	v_lshlrev_b32_e32 v9, 8, v10
	v_lshlrev_b32_e32 v8, 4, v8
	v_add3_u32 v8, v244, v9, v8
	ds_read_b128 v[68:71], v8
	v_add_u32_e32 v10, 8, v3
	v_ashrrev_i32_e32 v6, 3, v10
	v_ashrrev_i32_e32 v7, 31, v6
	v_lshl_add_u64 v[6:7], v[176:177], 0, v[6:7]
	v_and_or_b32 v8, v10, 7, s85
	v_lshlrev_b64 v[6:7], 11, v[6:7]
	v_lshlrev_b32_e32 v8, 7, v8
	v_or3_b32 v6, v6, v8, v0
	v_lshlrev_b64 v[20:21], 1, v[6:7]
	v_lshl_add_u64 v[6:7], s[86:87], 0, v[20:21]
	global_load_dwordx4 v[40:43], v[6:7], off
	v_bitop3_b32 v8, v10, v2, 15 bitop3:0x6c
	v_lshlrev_b32_e32 v9, 8, v10
	v_lshlrev_b32_e32 v8, 4, v8
	v_add3_u32 v8, v244, v9, v8
	ds_read_b128 v[72:75], v8
	v_add_u32_e32 v10, 12, v3
	v_ashrrev_i32_e32 v6, 3, v10
	v_ashrrev_i32_e32 v7, 31, v6
	v_lshl_add_u64 v[6:7], v[176:177], 0, v[6:7]
	v_and_or_b32 v8, v10, 7, s85
	v_lshlrev_b64 v[6:7], 11, v[6:7]
	v_lshlrev_b32_e32 v8, 7, v8
	v_or3_b32 v6, v6, v8, v0
	v_lshlrev_b64 v[22:23], 1, v[6:7]
	v_lshl_add_u64 v[6:7], s[86:87], 0, v[22:23]
	global_load_dwordx4 v[44:47], v[6:7], off
	v_bitop3_b32 v8, v10, v2, 15 bitop3:0x6c
	v_lshlrev_b32_e32 v9, 8, v10
	v_lshlrev_b32_e32 v8, 4, v8
	v_add3_u32 v8, v244, v9, v8
	ds_read_b128 v[76:79], v8
	v_add_u32_e32 v10, 16, v3
	v_ashrrev_i32_e32 v6, 3, v10
	v_ashrrev_i32_e32 v7, 31, v6
	v_lshl_add_u64 v[6:7], v[176:177], 0, v[6:7]
	v_and_or_b32 v8, v10, 7, s85
	v_lshlrev_b64 v[6:7], 11, v[6:7]
	v_lshlrev_b32_e32 v8, 7, v8
	v_or3_b32 v6, v6, v8, v0
	v_lshlrev_b64 v[24:25], 1, v[6:7]
	v_lshl_add_u64 v[6:7], s[86:87], 0, v[24:25]
	global_load_dwordx4 v[48:51], v[6:7], off
	v_bitop3_b32 v8, v10, v2, 15 bitop3:0x6c
	v_lshlrev_b32_e32 v9, 8, v10
	v_lshlrev_b32_e32 v8, 4, v8
	v_add3_u32 v8, v244, v9, v8
	ds_read_b128 v[80:83], v8
	v_add_u32_e32 v10, 20, v3
	v_ashrrev_i32_e32 v6, 3, v10
	v_ashrrev_i32_e32 v7, 31, v6
	v_lshl_add_u64 v[6:7], v[176:177], 0, v[6:7]
	v_and_or_b32 v8, v10, 7, s85
	v_lshlrev_b64 v[6:7], 11, v[6:7]
	v_lshlrev_b32_e32 v8, 7, v8
	v_or3_b32 v6, v6, v8, v0
	v_lshlrev_b64 v[26:27], 1, v[6:7]
	v_lshl_add_u64 v[6:7], s[86:87], 0, v[26:27]
	global_load_dwordx4 v[52:55], v[6:7], off
	v_bitop3_b32 v8, v10, v2, 15 bitop3:0x6c
	v_lshlrev_b32_e32 v9, 8, v10
	v_lshlrev_b32_e32 v8, 4, v8
	v_add3_u32 v8, v244, v9, v8
	ds_read_b128 v[84:87], v8
	v_add_u32_e32 v10, 24, v3
	v_ashrrev_i32_e32 v6, 3, v10
	v_ashrrev_i32_e32 v7, 31, v6
	v_lshl_add_u64 v[6:7], v[176:177], 0, v[6:7]
	v_and_or_b32 v8, v10, 7, s85
	v_lshlrev_b64 v[6:7], 11, v[6:7]
	v_lshlrev_b32_e32 v8, 7, v8
	v_or3_b32 v6, v6, v8, v0
	v_lshlrev_b64 v[28:29], 1, v[6:7]
	v_lshl_add_u64 v[6:7], s[86:87], 0, v[28:29]
	global_load_dwordx4 v[56:59], v[6:7], off
	v_bitop3_b32 v8, v10, v2, 15 bitop3:0x6c
	v_lshlrev_b32_e32 v9, 8, v10
	v_lshlrev_b32_e32 v8, 4, v8
	v_add3_u32 v8, v244, v9, v8
	ds_read_b128 v[88:91], v8
	v_add_u32_e32 v10, 28, v3
	v_ashrrev_i32_e32 v6, 3, v10
	v_ashrrev_i32_e32 v7, 31, v6
	v_lshl_add_u64 v[6:7], v[176:177], 0, v[6:7]
	v_and_or_b32 v8, v10, 7, s85
	v_lshlrev_b64 v[6:7], 11, v[6:7]
	v_lshlrev_b32_e32 v8, 7, v8
	v_or3_b32 v6, v6, v8, v0
	v_lshlrev_b64 v[30:31], 1, v[6:7]
	v_lshl_add_u64 v[6:7], s[86:87], 0, v[30:31]
	global_load_dwordx4 v[60:63], v[6:7], off
	v_bitop3_b32 v8, v10, v2, 15 bitop3:0x6c
	v_lshlrev_b32_e32 v9, 8, v10
	v_lshlrev_b32_e32 v8, 4, v8
	v_add3_u32 v8, v244, v9, v8
	ds_read_b128 v[92:95], v8
	s_waitcnt vmcnt(7) lgkmcnt(7)
	v_lshlrev_b32_e32 v12, 16, v64
	v_and_b32_e32 v13, 0xffff0000, v64
	v_lshlrev_b32_e32 v14, 16, v32
	v_and_b32_e32 v15, 0xffff0000, v32
	v_pk_fma_f32 v[12:13], v[96:97], v[14:15], v[12:13] op_sel_hi:[0,1,1]
	v_cvt_pk_bf16_f32 v64, v12, v13
	v_lshlrev_b32_e32 v12, 16, v65
	v_and_b32_e32 v13, 0xffff0000, v65
	v_lshlrev_b32_e32 v14, 16, v33
	v_and_b32_e32 v15, 0xffff0000, v33
	v_pk_fma_f32 v[12:13], v[96:97], v[14:15], v[12:13] op_sel_hi:[0,1,1]
	v_cvt_pk_bf16_f32 v65, v12, v13
	v_lshlrev_b32_e32 v12, 16, v66
	v_and_b32_e32 v13, 0xffff0000, v66
	v_lshlrev_b32_e32 v14, 16, v34
	v_and_b32_e32 v15, 0xffff0000, v34
	v_pk_fma_f32 v[12:13], v[96:97], v[14:15], v[12:13] op_sel_hi:[0,1,1]
	v_cvt_pk_bf16_f32 v66, v12, v13
	v_lshlrev_b32_e32 v12, 16, v67
	v_and_b32_e32 v13, 0xffff0000, v67
	v_lshlrev_b32_e32 v14, 16, v35
	v_and_b32_e32 v15, 0xffff0000, v35
	v_pk_fma_f32 v[12:13], v[96:97], v[14:15], v[12:13] op_sel_hi:[0,1,1]
	v_cvt_pk_bf16_f32 v67, v12, v13
	v_lshl_add_u64 v[6:7], s[82:83], 0, v[16:17]
	global_store_dwordx4 v[6:7], v[64:67], off
	s_waitcnt vmcnt(6) lgkmcnt(6)
; DI float bflo(unsigned w) { return __uint_as_float(w << 16); }
; DI float bfhi(unsigned w) { return __uint_as_float(w & 0xffff0000u); }
; DI void slc_block(const Params& p, int it, int tid, int wid, int lane) {
;     ...
;     for (int i = 0; i < 8; ++i) {
;       const int row = srow + 4 * i;
;       const uint4 v = lds_row_chunk(wl, row, sch);
;       const float2 gg = reinterpret_cast<const float2*>(wl + 8192)[row];
;       const size_t ro = (tokbase + t0 + 4 * wid + (row >> 3)) * 2048 + (size_t)(8 * g + (row & 7)) * 128 + sch * 8;
;       const uint4 ww = *reinterpret_cast<const uint4*>((const u16*)(p.ws + OFF_R3) + ro);
;       uint4 y;
;       y.x = pk2(bflo(v.x) + gg.y * bflo(ww.x), bfhi(v.x) + gg.y * bfhi(ww.x));
;       y.y = pk2(bflo(v.y) + gg.y * bflo(ww.y), bfhi(v.y) + gg.y * bfhi(ww.y));
;       y.z = pk2(bflo(v.z) + gg.y * bflo(ww.z), bfhi(v.z) + gg.y * bfhi(ww.z));
;       y.w = pk2(bflo(v.w) + gg.y * bflo(ww.w), bfhi(v.w) + gg.y * bfhi(ww.w));
;       *reinterpret_cast<uint4*>((u16*)(p.ws + OFF_YB) + ro) = y;
	v_lshlrev_b32_e32 v12, 16, v68
	v_and_b32_e32 v13, 0xffff0000, v68
	v_lshlrev_b32_e32 v14, 16, v36
	v_and_b32_e32 v15, 0xffff0000, v36
	v_pk_fma_f32 v[12:13], v[98:99], v[14:15], v[12:13] op_sel_hi:[0,1,1]
	v_cvt_pk_bf16_f32 v68, v12, v13
	v_lshlrev_b32_e32 v12, 16, v69
	v_and_b32_e32 v13, 0xffff0000, v69
	v_lshlrev_b32_e32 v14, 16, v37
	v_and_b32_e32 v15, 0xffff0000, v37
	v_pk_fma_f32 v[12:13], v[98:99], v[14:15], v[12:13] op_sel_hi:[0,1,1]
	v_cvt_pk_bf16_f32 v69, v12, v13
	v_lshlrev_b32_e32 v12, 16, v70
	v_and_b32_e32 v13, 0xffff0000, v70
	v_lshlrev_b32_e32 v14, 16, v38
	v_and_b32_e32 v15, 0xffff0000, v38
	v_pk_fma_f32 v[12:13], v[98:99], v[14:15], v[12:13] op_sel_hi:[0,1,1]
	v_cvt_pk_bf16_f32 v70, v12, v13
	v_lshlrev_b32_e32 v12, 16, v71
	v_and_b32_e32 v13, 0xffff0000, v71
	v_lshlrev_b32_e32 v14, 16, v39
	v_and_b32_e32 v15, 0xffff0000, v39
	v_pk_fma_f32 v[12:13], v[98:99], v[14:15], v[12:13] op_sel_hi:[0,1,1]
	v_cvt_pk_bf16_f32 v71, v12, v13
	v_lshl_add_u64 v[6:7], s[82:83], 0, v[18:19]
	global_store_dwordx4 v[6:7], v[68:71], off
	s_waitcnt vmcnt(5) lgkmcnt(5)
	v_lshlrev_b32_e32 v12, 16, v72
	v_and_b32_e32 v13, 0xffff0000, v72
	v_lshlrev_b32_e32 v14, 16, v40
	v_and_b32_e32 v15, 0xffff0000, v40
	v_pk_fma_f32 v[12:13], v[100:101], v[14:15], v[12:13] op_sel_hi:[0,1,1]
	v_cvt_pk_bf16_f32 v72, v12, v13
	v_lshlrev_b32_e32 v12, 16, v73
	v_and_b32_e32 v13, 0xffff0000, v73
	v_lshlrev_b32_e32 v14, 16, v41
	v_and_b32_e32 v15, 0xffff0000, v41
	v_pk_fma_f32 v[12:13], v[100:101], v[14:15], v[12:13] op_sel_hi:[0,1,1]
	v_cvt_pk_bf16_f32 v73, v12, v13
	v_lshlrev_b32_e32 v12, 16, v74
	v_and_b32_e32 v13, 0xffff0000, v74
	v_lshlrev_b32_e32 v14, 16, v42
	v_and_b32_e32 v15, 0xffff0000, v42
	v_pk_fma_f32 v[12:13], v[100:101], v[14:15], v[12:13] op_sel_hi:[0,1,1]
	v_cvt_pk_bf16_f32 v74, v12, v13
	v_lshlrev_b32_e32 v12, 16, v75
	v_and_b32_e32 v13, 0xffff0000, v75
	v_lshlrev_b32_e32 v14, 16, v43
	v_and_b32_e32 v15, 0xffff0000, v43
	v_pk_fma_f32 v[12:13], v[100:101], v[14:15], v[12:13] op_sel_hi:[0,1,1]
	v_cvt_pk_bf16_f32 v75, v12, v13
	v_lshl_add_u64 v[6:7], s[82:83], 0, v[20:21]
	global_store_dwordx4 v[6:7], v[72:75], off
	s_waitcnt vmcnt(4) lgkmcnt(4)
	v_lshlrev_b32_e32 v12, 16, v76
	v_and_b32_e32 v13, 0xffff0000, v76
	v_lshlrev_b32_e32 v14, 16, v44
	v_and_b32_e32 v15, 0xffff0000, v44
	v_pk_fma_f32 v[12:13], v[102:103], v[14:15], v[12:13] op_sel_hi:[0,1,1]
	v_cvt_pk_bf16_f32 v76, v12, v13
	v_lshlrev_b32_e32 v12, 16, v77
	v_and_b32_e32 v13, 0xffff0000, v77
	v_lshlrev_b32_e32 v14, 16, v45
	v_and_b32_e32 v15, 0xffff0000, v45
	v_pk_fma_f32 v[12:13], v[102:103], v[14:15], v[12:13] op_sel_hi:[0,1,1]
	v_cvt_pk_bf16_f32 v77, v12, v13
	v_lshlrev_b32_e32 v12, 16, v78
	v_and_b32_e32 v13, 0xffff0000, v78
	v_lshlrev_b32_e32 v14, 16, v46
	v_and_b32_e32 v15, 0xffff0000, v46
	v_pk_fma_f32 v[12:13], v[102:103], v[14:15], v[12:13] op_sel_hi:[0,1,1]
	v_cvt_pk_bf16_f32 v78, v12, v13
	v_lshlrev_b32_e32 v12, 16, v79
	v_and_b32_e32 v13, 0xffff0000, v79
	v_lshlrev_b32_e32 v14, 16, v47
	v_and_b32_e32 v15, 0xffff0000, v47
	v_pk_fma_f32 v[12:13], v[102:103], v[14:15], v[12:13] op_sel_hi:[0,1,1]
	v_cvt_pk_bf16_f32 v79, v12, v13
	v_lshl_add_u64 v[6:7], s[82:83], 0, v[22:23]
	global_store_dwordx4 v[6:7], v[76:79], off
	s_waitcnt vmcnt(3) lgkmcnt(3)
	v_lshlrev_b32_e32 v12, 16, v80
	v_and_b32_e32 v13, 0xffff0000, v80
	v_lshlrev_b32_e32 v14, 16, v48
	v_and_b32_e32 v15, 0xffff0000, v48
	v_pk_fma_f32 v[12:13], v[104:105], v[14:15], v[12:13] op_sel_hi:[0,1,1]
	v_cvt_pk_bf16_f32 v80, v12, v13
	v_lshlrev_b32_e32 v12, 16, v81
	v_and_b32_e32 v13, 0xffff0000, v81
	v_lshlrev_b32_e32 v14, 16, v49
	v_and_b32_e32 v15, 0xffff0000, v49
	v_pk_fma_f32 v[12:13], v[104:105], v[14:15], v[12:13] op_sel_hi:[0,1,1]
	v_cvt_pk_bf16_f32 v81, v12, v13
	v_lshlrev_b32_e32 v12, 16, v82
	v_and_b32_e32 v13, 0xffff0000, v82
	v_lshlrev_b32_e32 v14, 16, v50
	v_and_b32_e32 v15, 0xffff0000, v50
	v_pk_fma_f32 v[12:13], v[104:105], v[14:15], v[12:13] op_sel_hi:[0,1,1]
	v_cvt_pk_bf16_f32 v82, v12, v13
	v_lshlrev_b32_e32 v12, 16, v83
	v_and_b32_e32 v13, 0xffff0000, v83
	v_lshlrev_b32_e32 v14, 16, v51
	v_and_b32_e32 v15, 0xffff0000, v51
	v_pk_fma_f32 v[12:13], v[104:105], v[14:15], v[12:13] op_sel_hi:[0,1,1]
	v_cvt_pk_bf16_f32 v83, v12, v13
	v_lshl_add_u64 v[6:7], s[82:83], 0, v[24:25]
	global_store_dwordx4 v[6:7], v[80:83], off
	s_waitcnt vmcnt(2) lgkmcnt(2)
; DI float bflo(unsigned w) { return __uint_as_float(w << 16); }
; DI float bfhi(unsigned w) { return __uint_as_float(w & 0xffff0000u); }
; DI void slc_block(const Params& p, int it, int tid, int wid, int lane) {
;     ...
;     for (int i = 0; i < 8; ++i) {
;       const int row = srow + 4 * i;
;       const uint4 v = lds_row_chunk(wl, row, sch);
;       const float2 gg = reinterpret_cast<const float2*>(wl + 8192)[row];
;       const size_t ro = (tokbase + t0 + 4 * wid + (row >> 3)) * 2048 + (size_t)(8 * g + (row & 7)) * 128 + sch * 8;
;       const uint4 ww = *reinterpret_cast<const uint4*>((const u16*)(p.ws + OFF_R3) + ro);
;       uint4 y;
;       y.x = pk2(bflo(v.x) + gg.y * bflo(ww.x), bfhi(v.x) + gg.y * bfhi(ww.x));
;       y.y = pk2(bflo(v.y) + gg.y * bflo(ww.y), bfhi(v.y) + gg.y * bfhi(ww.y));
;       y.z = pk2(bflo(v.z) + gg.y * bflo(ww.z), bfhi(v.z) + gg.y * bfhi(ww.z));
;       y.w = pk2(bflo(v.w) + gg.y * bflo(ww.w), bfhi(v.w) + gg.y * bfhi(ww.w));
;       *reinterpret_cast<uint4*>((u16*)(p.ws + OFF_YB) + ro) = y;
;     }
;   }
;   __syncthreads();
	v_lshlrev_b32_e32 v12, 16, v84
	v_and_b32_e32 v13, 0xffff0000, v84
	v_lshlrev_b32_e32 v14, 16, v52
	v_and_b32_e32 v15, 0xffff0000, v52
	v_pk_fma_f32 v[12:13], v[106:107], v[14:15], v[12:13] op_sel_hi:[0,1,1]
	v_cvt_pk_bf16_f32 v84, v12, v13
	v_lshlrev_b32_e32 v12, 16, v85
	v_and_b32_e32 v13, 0xffff0000, v85
	v_lshlrev_b32_e32 v14, 16, v53
	v_and_b32_e32 v15, 0xffff0000, v53
	v_pk_fma_f32 v[12:13], v[106:107], v[14:15], v[12:13] op_sel_hi:[0,1,1]
	v_cvt_pk_bf16_f32 v85, v12, v13
	v_lshlrev_b32_e32 v12, 16, v86
	v_and_b32_e32 v13, 0xffff0000, v86
	v_lshlrev_b32_e32 v14, 16, v54
	v_and_b32_e32 v15, 0xffff0000, v54
	v_pk_fma_f32 v[12:13], v[106:107], v[14:15], v[12:13] op_sel_hi:[0,1,1]
	v_cvt_pk_bf16_f32 v86, v12, v13
	v_lshlrev_b32_e32 v12, 16, v87
	v_and_b32_e32 v13, 0xffff0000, v87
	v_lshlrev_b32_e32 v14, 16, v55
	v_and_b32_e32 v15, 0xffff0000, v55
	v_pk_fma_f32 v[12:13], v[106:107], v[14:15], v[12:13] op_sel_hi:[0,1,1]
	v_cvt_pk_bf16_f32 v87, v12, v13
	v_lshl_add_u64 v[6:7], s[82:83], 0, v[26:27]
	global_store_dwordx4 v[6:7], v[84:87], off
	s_waitcnt vmcnt(1) lgkmcnt(1)
	v_lshlrev_b32_e32 v12, 16, v88
	v_and_b32_e32 v13, 0xffff0000, v88
	v_lshlrev_b32_e32 v14, 16, v56
	v_and_b32_e32 v15, 0xffff0000, v56
	v_pk_fma_f32 v[12:13], v[108:109], v[14:15], v[12:13] op_sel_hi:[0,1,1]
	v_cvt_pk_bf16_f32 v88, v12, v13
	v_lshlrev_b32_e32 v12, 16, v89
	v_and_b32_e32 v13, 0xffff0000, v89
	v_lshlrev_b32_e32 v14, 16, v57
	v_and_b32_e32 v15, 0xffff0000, v57
	v_pk_fma_f32 v[12:13], v[108:109], v[14:15], v[12:13] op_sel_hi:[0,1,1]
	v_cvt_pk_bf16_f32 v89, v12, v13
	v_lshlrev_b32_e32 v12, 16, v90
	v_and_b32_e32 v13, 0xffff0000, v90
	v_lshlrev_b32_e32 v14, 16, v58
	v_and_b32_e32 v15, 0xffff0000, v58
	v_pk_fma_f32 v[12:13], v[108:109], v[14:15], v[12:13] op_sel_hi:[0,1,1]
	v_cvt_pk_bf16_f32 v90, v12, v13
	v_lshlrev_b32_e32 v12, 16, v91
	v_and_b32_e32 v13, 0xffff0000, v91
	v_lshlrev_b32_e32 v14, 16, v59
	v_and_b32_e32 v15, 0xffff0000, v59
	v_pk_fma_f32 v[12:13], v[108:109], v[14:15], v[12:13] op_sel_hi:[0,1,1]
	v_cvt_pk_bf16_f32 v91, v12, v13
	v_lshl_add_u64 v[6:7], s[82:83], 0, v[28:29]
	global_store_dwordx4 v[6:7], v[88:91], off
	s_waitcnt vmcnt(0) lgkmcnt(0)
	v_lshlrev_b32_e32 v12, 16, v92
	v_and_b32_e32 v13, 0xffff0000, v92
	v_lshlrev_b32_e32 v14, 16, v60
	v_and_b32_e32 v15, 0xffff0000, v60
	v_pk_fma_f32 v[12:13], v[110:111], v[14:15], v[12:13] op_sel_hi:[0,1,1]
	v_cvt_pk_bf16_f32 v92, v12, v13
	v_lshlrev_b32_e32 v12, 16, v93
	v_and_b32_e32 v13, 0xffff0000, v93
	v_lshlrev_b32_e32 v14, 16, v61
	v_and_b32_e32 v15, 0xffff0000, v61
	v_pk_fma_f32 v[12:13], v[110:111], v[14:15], v[12:13] op_sel_hi:[0,1,1]
	v_cvt_pk_bf16_f32 v93, v12, v13
	v_lshlrev_b32_e32 v12, 16, v94
	v_and_b32_e32 v13, 0xffff0000, v94
	v_lshlrev_b32_e32 v14, 16, v62
	v_and_b32_e32 v15, 0xffff0000, v62
	v_pk_fma_f32 v[12:13], v[110:111], v[14:15], v[12:13] op_sel_hi:[0,1,1]
	v_cvt_pk_bf16_f32 v94, v12, v13
	v_lshlrev_b32_e32 v12, 16, v95
	v_and_b32_e32 v13, 0xffff0000, v95
	v_lshlrev_b32_e32 v14, 16, v63
	v_and_b32_e32 v15, 0xffff0000, v63
	v_pk_fma_f32 v[12:13], v[110:111], v[14:15], v[12:13] op_sel_hi:[0,1,1]
	v_cvt_pk_bf16_f32 v95, v12, v13
	v_lshl_add_u64 v[6:7], s[82:83], 0, v[30:31]
	global_store_dwordx4 v[6:7], v[92:95], off
	s_cmpk_gt_i32 s29, 0x3ff
	s_barrier
	s_cbranch_scc1 .LBB0_230
